# combo3 + NORM bias-GEMV butterflies: 5 of 6 reduction steps via permlane32/16_swap and DPP (row_ror:8, quad_perm) instead of ds_bpermute, same order
# speedup vs baseline: 1.0053x; 1.0014x over previous
.LBB0_178:
	s_waitcnt vmcnt(8)
	v_lshlrev_b32_e32 v0, 16, v198
	s_nop 0
	v_and_b32_e32 v169, 0xffff0000, v202
	v_lshlrev_b32_e32 v163, 16, v202
	v_and_b32_e32 v161, 0xffff0000, v198
	v_and_b32_e32 v170, 0xffff0000, v204
	s_waitcnt lgkmcnt(14)
	v_mul_f32_e32 v140, v3, v169
	v_lshlrev_b32_e32 v167, 16, v203
	v_lshlrev_b32_e32 v164, 16, v204
	v_fmac_f32_e32 v140, v2, v163
	v_mul_f32_e32 v141, v7, v170
	v_and_b32_e32 v165, 0xffff0000, v203
	v_lshlrev_b32_e32 v168, 16, v205
	v_fmac_f32_e32 v140, v4, v167
	v_fmac_f32_e32 v141, v6, v164
	v_and_b32_e32 v166, 0xffff0000, v205
	v_fmac_f32_e32 v140, v5, v165
	v_fmac_f32_e32 v141, v8, v168
	v_add_f32_e32 v140, 0, v140
	v_fmac_f32_e32 v141, v9, v166
	v_add_f32_e32 v140, v141, v140
	v_mul_f32_e32 v141, v11, v161
	v_lshlrev_b32_e32 v159, 16, v199
	v_fmac_f32_e32 v141, v10, v0
	v_and_b32_e32 v157, 0xffff0000, v199
	v_fmac_f32_e32 v141, v12, v159
	v_and_b32_e32 v162, 0xffff0000, v200
	v_fmac_f32_e32 v141, v13, v157
	s_waitcnt lgkmcnt(0)
	v_lshlrev_b32_e32 v156, 16, v200
	v_add_f32_e32 v140, v141, v140
	v_mul_f32_e32 v141, v15, v162
	v_lshlrev_b32_e32 v160, 16, v201
	v_fmac_f32_e32 v141, v14, v156
	v_and_b32_e32 v158, 0xffff0000, v201
	v_lshl_add_u64 v[244:245], v[244:245], 0, s[24:25]
	global_load_dwordx4 v[198:201], v[244:245], off offset:16
	global_load_dwordx4 v[202:205], v[244:245], off
	v_fmac_f32_e32 v141, v16, v160
	v_fmac_f32_e32 v141, v17, v158
	v_add_f32_e32 v180, v141, v140
	v_mul_f32_e32 v171, v19, v169
	v_fmac_f32_e32 v171, v18, v163
	s_waitcnt lgkmcnt(0)
	v_mul_f32_e32 v172, v23, v170
	v_fmac_f32_e32 v171, v20, v167
	v_fmac_f32_e32 v172, v22, v164
	v_fmac_f32_e32 v171, v21, v165
	v_fmac_f32_e32 v172, v24, v168
	v_add_f32_e32 v171, 0, v171
	v_fmac_f32_e32 v172, v25, v166
	v_add_f32_e32 v171, v172, v171
	v_mul_f32_e32 v172, v27, v161
	v_fmac_f32_e32 v172, v26, v0
	v_fmac_f32_e32 v172, v28, v159
	v_fmac_f32_e32 v172, v29, v157
	v_add_f32_e32 v171, v172, v171
	v_mul_f32_e32 v172, v31, v162
	v_fmac_f32_e32 v172, v30, v156
	v_fmac_f32_e32 v172, v32, v160
	v_fmac_f32_e32 v172, v33, v158
	v_add_f32_e32 v181, v172, v171
	v_mul_f32_e32 v171, v35, v169
	v_fmac_f32_e32 v171, v34, v163
	s_waitcnt lgkmcnt(0)
	v_mul_f32_e32 v172, v39, v170
	v_fmac_f32_e32 v171, v36, v167
	v_fmac_f32_e32 v172, v38, v164
	v_fmac_f32_e32 v171, v37, v165
	v_fmac_f32_e32 v172, v40, v168
	v_add_f32_e32 v171, 0, v171
	v_fmac_f32_e32 v172, v41, v166
	v_add_f32_e32 v171, v172, v171
	v_mul_f32_e32 v172, v43, v161
	v_fmac_f32_e32 v172, v42, v0
	v_fmac_f32_e32 v172, v44, v159
	v_fmac_f32_e32 v172, v45, v157
	v_add_f32_e32 v171, v172, v171
	v_mul_f32_e32 v172, v47, v162
	v_fmac_f32_e32 v172, v46, v156
	v_fmac_f32_e32 v172, v48, v160
	v_fmac_f32_e32 v172, v49, v158
	v_add_f32_e32 v182, v172, v171
	v_mul_f32_e32 v171, v51, v169
	v_fmac_f32_e32 v171, v50, v163
	s_waitcnt lgkmcnt(0)
	v_mul_f32_e32 v172, v55, v170
	v_fmac_f32_e32 v171, v52, v167
	v_fmac_f32_e32 v172, v54, v164
	v_fmac_f32_e32 v171, v53, v165
	v_fmac_f32_e32 v172, v56, v168
	v_add_f32_e32 v171, 0, v171
	v_fmac_f32_e32 v172, v57, v166
	v_add_f32_e32 v171, v172, v171
	v_mul_f32_e32 v172, v59, v161
	v_fmac_f32_e32 v172, v58, v0
	v_fmac_f32_e32 v172, v60, v159
	v_fmac_f32_e32 v172, v61, v157
	v_add_f32_e32 v171, v172, v171
	v_mul_f32_e32 v172, v63, v162
	v_fmac_f32_e32 v172, v62, v156
	v_fmac_f32_e32 v172, v64, v160
	v_fmac_f32_e32 v172, v65, v158
	v_add_f32_e32 v183, v172, v171
	v_mul_f32_e32 v171, v67, v169
	v_fmac_f32_e32 v171, v66, v163
	s_waitcnt lgkmcnt(0)
	v_mul_f32_e32 v172, v71, v170
	v_fmac_f32_e32 v171, v68, v167
	v_fmac_f32_e32 v172, v70, v164
	v_fmac_f32_e32 v171, v69, v165
	v_fmac_f32_e32 v172, v72, v168
	v_add_f32_e32 v171, 0, v171
	v_fmac_f32_e32 v172, v73, v166
	v_add_f32_e32 v171, v172, v171
	v_mul_f32_e32 v172, v75, v161
	v_fmac_f32_e32 v172, v74, v0
	v_fmac_f32_e32 v172, v76, v159
	v_fmac_f32_e32 v172, v77, v157
	v_add_f32_e32 v171, v172, v171
	v_mul_f32_e32 v172, v79, v162
	v_fmac_f32_e32 v172, v78, v156
	v_fmac_f32_e32 v172, v80, v160
	v_fmac_f32_e32 v172, v81, v158
	v_add_f32_e32 v184, v172, v171
	v_mul_f32_e32 v171, v83, v169
	v_fmac_f32_e32 v171, v82, v163
	s_waitcnt lgkmcnt(0)
	v_mul_f32_e32 v172, v87, v170
	v_fmac_f32_e32 v171, v84, v167
	v_fmac_f32_e32 v172, v86, v164
	v_fmac_f32_e32 v171, v85, v165
	v_fmac_f32_e32 v172, v88, v168
	v_add_f32_e32 v171, 0, v171
	v_fmac_f32_e32 v172, v89, v166
	v_add_f32_e32 v171, v172, v171
	v_mul_f32_e32 v172, v91, v161
	v_fmac_f32_e32 v172, v90, v0
	v_fmac_f32_e32 v172, v92, v159
	v_fmac_f32_e32 v172, v93, v157
	v_add_f32_e32 v171, v172, v171
	v_mul_f32_e32 v172, v95, v162
	v_fmac_f32_e32 v172, v94, v156
	v_fmac_f32_e32 v172, v96, v160
	v_fmac_f32_e32 v172, v97, v158
	v_add_f32_e32 v185, v172, v171
	v_mul_f32_e32 v171, v99, v169
	v_fmac_f32_e32 v171, v98, v163
	s_waitcnt lgkmcnt(0)
	v_mul_f32_e32 v172, v103, v170
	v_fmac_f32_e32 v171, v100, v167
	v_fmac_f32_e32 v172, v102, v164
	v_fmac_f32_e32 v171, v101, v165
	v_fmac_f32_e32 v172, v104, v168
	v_add_f32_e32 v171, 0, v171
	v_fmac_f32_e32 v172, v105, v166
	v_add_f32_e32 v171, v172, v171
	v_mul_f32_e32 v172, v107, v161
	v_fmac_f32_e32 v172, v106, v0
	v_fmac_f32_e32 v172, v108, v159
	v_fmac_f32_e32 v172, v109, v157
	v_add_f32_e32 v171, v172, v171
	v_mul_f32_e32 v172, v111, v162
	v_fmac_f32_e32 v172, v110, v156
	v_fmac_f32_e32 v172, v112, v160
	v_fmac_f32_e32 v172, v113, v158
	v_add_f32_e32 v186, v172, v171
	v_mul_f32_e32 v169, v115, v169
	v_fmac_f32_e32 v169, v114, v163
	v_fmac_f32_e32 v169, v116, v167
	v_mul_f32_e32 v161, v123, v161
	v_fmac_f32_e32 v169, v117, v165
	v_mul_f32_e32 v165, v119, v170
	v_fmac_f32_e32 v161, v122, v0
	v_fmac_f32_e32 v165, v118, v164
	v_fmac_f32_e32 v161, v124, v159
	v_fmac_f32_e32 v165, v120, v168
	v_fmac_f32_e32 v161, v125, v157
	v_mul_f32_e32 v157, v127, v162
	v_add_f32_e32 v163, 0, v169
	v_fmac_f32_e32 v165, v121, v166
	v_fmac_f32_e32 v157, v126, v156
	v_add_f32_e32 v163, v165, v163
	v_fmac_f32_e32 v157, v128, v160
	v_add_f32_e32 v0, v161, v163
	v_fmac_f32_e32 v157, v129, v158
	v_add_f32_e32 v187, v157, v0
	v_mov_b32_e32 v188, v180
	v_mov_b32_e32 v189, v181
	v_mov_b32_e32 v190, v182
	v_mov_b32_e32 v191, v183
	v_mov_b32_e32 v192, v184
	v_mov_b32_e32 v193, v185
	v_mov_b32_e32 v194, v186
	v_mov_b32_e32 v195, v187
	s_nop 1
	v_permlane32_swap_b32_e32 v188, v180
	v_permlane32_swap_b32_e32 v189, v181
	v_permlane32_swap_b32_e32 v190, v182
	v_permlane32_swap_b32_e32 v191, v183
	v_permlane32_swap_b32_e32 v192, v184
	v_permlane32_swap_b32_e32 v193, v185
	v_permlane32_swap_b32_e32 v194, v186
	v_permlane32_swap_b32_e32 v195, v187
	v_add_f32_e32 v180, v180, v188
	v_add_f32_e32 v181, v181, v189
	v_add_f32_e32 v182, v182, v190
	v_add_f32_e32 v183, v183, v191
	v_add_f32_e32 v184, v184, v192
	v_add_f32_e32 v185, v185, v193
	v_add_f32_e32 v186, v186, v194
	v_add_f32_e32 v187, v187, v195
	v_mov_b32_e32 v188, v180
	v_mov_b32_e32 v189, v181
	v_mov_b32_e32 v190, v182
	v_mov_b32_e32 v191, v183
	v_mov_b32_e32 v192, v184
	v_mov_b32_e32 v193, v185
	v_mov_b32_e32 v194, v186
	v_mov_b32_e32 v195, v187
	s_nop 1
	v_permlane16_swap_b32_e32 v188, v180
	v_permlane16_swap_b32_e32 v189, v181
	v_permlane16_swap_b32_e32 v190, v182
	v_permlane16_swap_b32_e32 v191, v183
	v_permlane16_swap_b32_e32 v192, v184
	v_permlane16_swap_b32_e32 v193, v185
	v_permlane16_swap_b32_e32 v194, v186
	v_permlane16_swap_b32_e32 v195, v187
	v_add_f32_e32 v180, v180, v188
	v_add_f32_e32 v181, v181, v189
	v_add_f32_e32 v182, v182, v190
	v_add_f32_e32 v183, v183, v191
	v_add_f32_e32 v184, v184, v192
	v_add_f32_e32 v185, v185, v193
	v_add_f32_e32 v186, v186, v194
	v_add_f32_e32 v187, v187, v195
	v_mov_b32_dpp v188, v180 row_ror:8 row_mask:0xf bank_mask:0xf
	v_mov_b32_dpp v189, v181 row_ror:8 row_mask:0xf bank_mask:0xf
	v_mov_b32_dpp v190, v182 row_ror:8 row_mask:0xf bank_mask:0xf
	v_mov_b32_dpp v191, v183 row_ror:8 row_mask:0xf bank_mask:0xf
	v_mov_b32_dpp v192, v184 row_ror:8 row_mask:0xf bank_mask:0xf
	v_mov_b32_dpp v193, v185 row_ror:8 row_mask:0xf bank_mask:0xf
	v_mov_b32_dpp v194, v186 row_ror:8 row_mask:0xf bank_mask:0xf
	v_mov_b32_dpp v195, v187 row_ror:8 row_mask:0xf bank_mask:0xf
	s_nop 0
	v_add_f32_e32 v180, v180, v188
	v_add_f32_e32 v181, v181, v189
	v_add_f32_e32 v182, v182, v190
	v_add_f32_e32 v183, v183, v191
	v_add_f32_e32 v184, v184, v192
	v_add_f32_e32 v185, v185, v193
	v_add_f32_e32 v186, v186, v194
	v_add_f32_e32 v187, v187, v195
	ds_bpermute_b32 v188, v149, v180
	ds_bpermute_b32 v189, v149, v181
	ds_bpermute_b32 v190, v149, v182
	ds_bpermute_b32 v191, v149, v183
	ds_bpermute_b32 v192, v149, v184
	ds_bpermute_b32 v193, v149, v185
	ds_bpermute_b32 v194, v149, v186
	ds_bpermute_b32 v195, v149, v187
	s_waitcnt lgkmcnt(0)
	v_add_f32_e32 v180, v180, v188
	v_add_f32_e32 v181, v181, v189
	v_add_f32_e32 v182, v182, v190
	v_add_f32_e32 v183, v183, v191
	v_add_f32_e32 v184, v184, v192
	v_add_f32_e32 v185, v185, v193
	v_add_f32_e32 v186, v186, v194
	v_add_f32_e32 v187, v187, v195
	v_mov_b32_dpp v188, v180 quad_perm:[2,3,0,1] row_mask:0xf bank_mask:0xf
	v_mov_b32_dpp v189, v181 quad_perm:[2,3,0,1] row_mask:0xf bank_mask:0xf
	v_mov_b32_dpp v190, v182 quad_perm:[2,3,0,1] row_mask:0xf bank_mask:0xf
	v_mov_b32_dpp v191, v183 quad_perm:[2,3,0,1] row_mask:0xf bank_mask:0xf
	v_mov_b32_dpp v192, v184 quad_perm:[2,3,0,1] row_mask:0xf bank_mask:0xf
	v_mov_b32_dpp v193, v185 quad_perm:[2,3,0,1] row_mask:0xf bank_mask:0xf
	v_mov_b32_dpp v194, v186 quad_perm:[2,3,0,1] row_mask:0xf bank_mask:0xf
	v_mov_b32_dpp v195, v187 quad_perm:[2,3,0,1] row_mask:0xf bank_mask:0xf
	s_nop 0
	v_add_f32_e32 v180, v180, v188
	v_add_f32_e32 v181, v181, v189
	v_add_f32_e32 v182, v182, v190
	v_add_f32_e32 v183, v183, v191
	v_add_f32_e32 v184, v184, v192
	v_add_f32_e32 v185, v185, v193
	v_add_f32_e32 v186, v186, v194
	v_add_f32_e32 v187, v187, v195
	v_mov_b32_dpp v188, v180 quad_perm:[1,0,3,2] row_mask:0xf bank_mask:0xf
	v_mov_b32_dpp v189, v181 quad_perm:[1,0,3,2] row_mask:0xf bank_mask:0xf
	v_mov_b32_dpp v190, v182 quad_perm:[1,0,3,2] row_mask:0xf bank_mask:0xf
	v_mov_b32_dpp v191, v183 quad_perm:[1,0,3,2] row_mask:0xf bank_mask:0xf
	v_mov_b32_dpp v192, v184 quad_perm:[1,0,3,2] row_mask:0xf bank_mask:0xf
	v_mov_b32_dpp v193, v185 quad_perm:[1,0,3,2] row_mask:0xf bank_mask:0xf
	v_mov_b32_dpp v194, v186 quad_perm:[1,0,3,2] row_mask:0xf bank_mask:0xf
	v_mov_b32_dpp v195, v187 quad_perm:[1,0,3,2] row_mask:0xf bank_mask:0xf
	s_nop 0
	v_add_f32_e32 v180, v180, v188
	v_add_f32_e32 v181, v181, v189
	v_add_f32_e32 v182, v182, v190
	v_add_f32_e32 v183, v183, v191
	v_add_f32_e32 v184, v184, v192
	v_add_f32_e32 v185, v185, v193
	v_add_f32_e32 v186, v186, v194
	v_add_f32_e32 v187, v187, v195
	v_lshl_add_u64 v[140:141], s[18:19], 0, v[136:137]
	s_and_saveexec_b64 s[2:3], s[38:39]
	s_cbranch_execz .LBB0_177
	v_add_co_u32_e32 v196, vcc, 0xf700000, v140
	s_nop 1
	v_addc_co_u32_e32 v197, vcc, 0, v141, vcc
	global_store_dword v[196:197], v180, off
	v_add_co_u32_e32 v196, vcc, 0xf704000, v140
	s_nop 1
	v_addc_co_u32_e32 v197, vcc, 0, v141, vcc
	global_store_dword v[196:197], v181, off
	v_add_co_u32_e32 v196, vcc, 0xf708000, v140
	s_nop 1
	v_addc_co_u32_e32 v197, vcc, 0, v141, vcc
	global_store_dword v[196:197], v182, off
	v_add_co_u32_e32 v196, vcc, 0xf70c000, v140
	s_nop 1
	v_addc_co_u32_e32 v197, vcc, 0, v141, vcc
	global_store_dword v[196:197], v183, off
	v_add_co_u32_e32 v196, vcc, 0xf710000, v140
	s_nop 1
	v_addc_co_u32_e32 v197, vcc, 0, v141, vcc
	global_store_dword v[196:197], v184, off
	v_add_co_u32_e32 v196, vcc, 0xf714000, v140
	s_nop 1
	v_addc_co_u32_e32 v197, vcc, 0, v141, vcc
	global_store_dword v[196:197], v185, off
	v_add_co_u32_e32 v196, vcc, 0xf718000, v140
	s_nop 1
	v_addc_co_u32_e32 v197, vcc, 0, v141, vcc
	global_store_dword v[196:197], v186, off
	v_add_co_u32_e32 v196, vcc, 0xf71c000, v140
	s_nop 1
	v_addc_co_u32_e32 v197, vcc, 0, v141, vcc
	global_store_dword v[196:197], v187, off
	s_branch .LBB0_177
